# merge g-GEMM (K=1024) loop: LDS-DMA global_load_lds double-buffered swizzled stage instead of register-staged single buffer
# speedup vs baseline: 1.0757x; 1.0150x over previous
.LBB0_105:
	v_mov_b32_e32 v3, v133
	s_lshl_b32 s6, s12, 20
	v_lshlrev_b32_e32 v0, 3, v3
	v_lshrrev_b32_e32 v4, 3, v3
	v_and_b32_e32 v156, 56, v0
	v_mul_lo_u32 v4, v4, s21
	v_add_lshl_u32 v168, v4, v156, 1
	v_add_u32_e32 v4, 0x100, v3
	v_lshrrev_b32_e32 v4, 3, v4
	v_mul_lo_u32 v4, v4, s21
	v_add_lshl_u32 v169, v4, v156, 1
	v_add_u32_e32 v4, 0x200, v3
	v_lshrrev_b32_e32 v4, 3, v4
	v_mul_lo_u32 v4, v4, s21
	v_add_lshl_u32 v170, v4, v156, 1
	v_add_u32_e32 v4, 0x300, v3
	v_lshrrev_b32_e32 v4, 3, v4
	v_mul_lo_u32 v4, v4, s21
	s_add_i32 s4, s11, s6
	v_and_b32_e32 v2, 31, v3
	v_lshlrev_b32_e32 v0, 7, v3
	v_add_lshl_u32 v171, v4, v156, 1
	v_lshrrev_b32_e32 v4, 1, v3
	s_mov_b32 s14, 0xfffffc0
	s_lshl_b32 s4, s4, 1
	v_and_b32_e32 v164, 0xfffffc00, v0
	v_and_or_b32 v5, v4, s14, v2
	v_and_b32_e32 v2, 16, v4
	s_add_u32 s4, s18, s4
	v_add_u32_e32 v165, 0x8000, v164
	v_add_u32_e32 v166, 0x10000, v164
	v_add_u32_e32 v167, 0x18000, v164
	v_mad_u64_u32 v[158:159], s[14:15], v5, s37, v[2:3]
	v_and_b32_e32 v3, 0x5f, v3
	s_mov_b32 s7, 1
	s_addc_u32 s5, s19, 0
	v_or_b32_e32 v0, v165, v156
	v_or_b32_e32 v160, v166, v156
	v_or_b32_e32 v162, v167, v156
	v_mad_u32_u24 v159, v3, s37, v2
	v_mov_b32_e32 v161, v156
	v_mov_b32_e32 v2, 0
	v_mov_b32_e32 v3, v152
	v_mov_b32_e32 v4, v152
	v_mov_b32_e32 v5, v152
	v_mov_b32_e32 v6, v152
	v_mov_b32_e32 v7, v152
	v_mov_b32_e32 v8, v152
	v_mov_b32_e32 v9, v152
	v_mov_b32_e32 v10, v152
	v_mov_b32_e32 v11, v152
	v_mov_b32_e32 v12, v152
	v_mov_b32_e32 v13, v152
	v_mov_b32_e32 v14, v152
	v_mov_b32_e32 v15, v152
	v_mov_b32_e32 v16, v152
	v_mov_b32_e32 v17, v152
	v_mov_b32_e32 v18, 0
	v_mov_b32_e32 v19, v152
	v_mov_b32_e32 v20, v152
	v_mov_b32_e32 v21, v152
	v_mov_b32_e32 v22, v152
	v_mov_b32_e32 v23, v152
	v_mov_b32_e32 v24, v152
	v_mov_b32_e32 v25, v152
	v_mov_b32_e32 v26, v152
	v_mov_b32_e32 v27, v152
	v_mov_b32_e32 v28, v152
	v_mov_b32_e32 v29, v152
	v_mov_b32_e32 v30, v152
	v_mov_b32_e32 v31, v152
	v_mov_b32_e32 v32, v152
	v_mov_b32_e32 v33, v152
	v_mov_b32_e32 v34, 0
	v_mov_b32_e32 v35, v152
	v_mov_b32_e32 v36, v152
	v_mov_b32_e32 v37, v152
	v_mov_b32_e32 v38, v152
	v_mov_b32_e32 v39, v152
	v_mov_b32_e32 v40, v152
	v_mov_b32_e32 v41, v152
	v_mov_b32_e32 v42, v152
	v_mov_b32_e32 v43, v152
	v_mov_b32_e32 v44, v152
	v_mov_b32_e32 v45, v152
	v_mov_b32_e32 v46, v152
	v_mov_b32_e32 v47, v152
	v_mov_b32_e32 v48, v152
	v_mov_b32_e32 v49, v152
	s_waitcnt vmcnt(3)
	v_mov_b32_e32 v50, 0
	s_waitcnt vmcnt(2)
	v_mov_b32_e32 v51, v152
	v_mov_b32_e32 v52, v152
	s_waitcnt vmcnt(1)
	v_mov_b32_e32 v53, v152
	v_mov_b32_e32 v54, v152
	v_mov_b32_e32 v55, v152
	v_mov_b32_e32 v56, v152
	v_mov_b32_e32 v57, v152
	v_mov_b32_e32 v58, v152
	v_mov_b32_e32 v59, v152
	v_mov_b32_e32 v60, v152
	v_mov_b32_e32 v61, v152
	v_mov_b32_e32 v62, v152
	v_mov_b32_e32 v63, v152
	v_mov_b32_e32 v64, v152
	v_mov_b32_e32 v65, v152
	v_and_b32_e32 v180, 63, v133
	v_lshrrev_b32_e32 v181, 6, v133
	v_lshlrev_b32_e32 v182, 12, v181
	v_lshrrev_b32_e32 v183, 3, v180
	v_readfirstlane_b32 s14, v182
	v_lshl_add_u32 v183, v181, 5, v183
	v_lshlrev_b32_e32 v183, 11, v183
	v_and_b32_e32 v214, 7, v180
	v_lshrrev_b32_e32 v215, 4, v180
	v_xor_b32_e32 v214, v214, v215
	v_xor_b32_e32 v215, 4, v214
	v_lshl_add_u32 v160, v214, 4, v183
	v_lshl_add_u32 v161, v215, 4, v183
	v_add_u32_e32 v161, 0x4000, v161
	v_add_u32_e32 v162, 0x8000, v160
	v_add_u32_e32 v163, 0x8000, v161
	v_and_b32_e32 v214, 31, v180
	v_lshrrev_b32_e32 v215, 5, v180
	v_bfe_u32 v232, v180, 1, 3
	v_xor_b32_e32 v215, v215, v232
	v_lshrrev_b32_e32 v233, 1, v181
	v_and_b32_e32 v234, 1, v181
	v_lshl_add_u32 v233, v233, 6, v214
	v_lshl_add_u32 v234, v234, 6, v214
	v_lshlrev_b32_e32 v233, 7, v233
	v_lshlrev_b32_e32 v234, 7, v234
	v_add_u32_e32 v234, 0x4000, v234
	v_lshl_add_u32 v172, v215, 4, v233
	v_lshl_add_u32 v176, v215, 4, v234
	v_xor_b32_e32 v235, 2, v215
	v_lshl_add_u32 v173, v235, 4, v233
	v_lshl_add_u32 v177, v235, 4, v234
	v_xor_b32_e32 v235, 4, v215
	v_lshl_add_u32 v174, v235, 4, v233
	v_lshl_add_u32 v178, v235, 4, v234
	v_xor_b32_e32 v235, 6, v215
	v_lshl_add_u32 v175, v235, 4, v233
	v_lshl_add_u32 v179, v235, 4, v234
	s_waitcnt lgkmcnt(0)
	s_barrier
	s_add_u32 m0, s14, 0x0
	s_nop 0
	global_load_lds_dwordx4 v160, s[38:39]
	s_add_u32 m0, s14, 0x400
	s_nop 0
	global_load_lds_dwordx4 v161, s[38:39]
	s_add_u32 m0, s14, 0x800
	s_nop 0
	global_load_lds_dwordx4 v162, s[38:39]
	s_add_u32 m0, s14, 0xc00
	s_nop 0
	global_load_lds_dwordx4 v163, s[38:39]
	s_add_u32 m0, s14, 0x4000
	s_nop 0
	global_load_lds_dwordx4 v160, s[4:5]
	s_add_u32 m0, s14, 0x4400
	s_nop 0
	global_load_lds_dwordx4 v161, s[4:5]
	s_add_u32 m0, s14, 0x4800
	s_nop 0
	global_load_lds_dwordx4 v162, s[4:5]
	s_add_u32 m0, s14, 0x4c00
	s_nop 0
	global_load_lds_dwordx4 v163, s[4:5]
	v_add_u32_e32 v160, 0x80, v160
	v_add_u32_e32 v161, 0x80, v161
	v_add_u32_e32 v162, 0x80, v162
	v_add_u32_e32 v163, 0x80, v163
	s_mov_b32 s7, 0
	s_waitcnt vmcnt(0)
.Lmgd_loop:
	s_barrier
	s_add_u32 m0, s14, 0x8000
	s_nop 0
	global_load_lds_dwordx4 v160, s[38:39]
	s_add_u32 m0, s14, 0x8400
	s_nop 0
	global_load_lds_dwordx4 v161, s[38:39]
	s_add_u32 m0, s14, 0x8800
	s_nop 0
	global_load_lds_dwordx4 v162, s[38:39]
	s_add_u32 m0, s14, 0x8c00
	s_nop 0
	global_load_lds_dwordx4 v163, s[38:39]
	s_add_u32 m0, s14, 0xc000
	s_nop 0
	global_load_lds_dwordx4 v160, s[4:5]
	s_add_u32 m0, s14, 0xc400
	s_nop 0
	global_load_lds_dwordx4 v161, s[4:5]
	s_add_u32 m0, s14, 0xc800
	s_nop 0
	global_load_lds_dwordx4 v162, s[4:5]
	s_add_u32 m0, s14, 0xcc00
	s_nop 0
	global_load_lds_dwordx4 v163, s[4:5]
	v_add_u32_e32 v160, 0x80, v160
	v_add_u32_e32 v161, 0x80, v161
	v_add_u32_e32 v162, 0x80, v162
	v_add_u32_e32 v163, 0x80, v163
	ds_read_b128 v[236:239], v172
	ds_read_b128 v[244:247], v176
	ds_read_b128 v[248:251], v176 offset:4096
	ds_read_b128 v[240:243], v172 offset:4096
	s_waitcnt lgkmcnt(2)
	v_mfma_f32_32x32x16_bf16 v[50:65], v[236:239], v[244:247], v[50:65]
	s_waitcnt lgkmcnt(1)
	v_mfma_f32_32x32x16_bf16 v[34:49], v[236:239], v[248:251], v[34:49]
	ds_read_b128 v[236:239], v173
	s_waitcnt lgkmcnt(1)
	v_mfma_f32_32x32x16_bf16 v[18:33], v[240:243], v[244:247], v[18:33]
	ds_read_b128 v[244:247], v177
	v_mfma_f32_32x32x16_bf16 v[2:17], v[240:243], v[248:251], v[2:17]
	ds_read_b128 v[248:251], v177 offset:4096
	ds_read_b128 v[240:243], v173 offset:4096
	s_waitcnt lgkmcnt(2)
	v_mfma_f32_32x32x16_bf16 v[50:65], v[236:239], v[244:247], v[50:65]
	s_waitcnt lgkmcnt(1)
	v_mfma_f32_32x32x16_bf16 v[34:49], v[236:239], v[248:251], v[34:49]
	ds_read_b128 v[236:239], v174
	s_waitcnt lgkmcnt(1)
	v_mfma_f32_32x32x16_bf16 v[18:33], v[240:243], v[244:247], v[18:33]
	ds_read_b128 v[244:247], v178
	v_mfma_f32_32x32x16_bf16 v[2:17], v[240:243], v[248:251], v[2:17]
	ds_read_b128 v[248:251], v178 offset:4096
	ds_read_b128 v[240:243], v174 offset:4096
	s_waitcnt lgkmcnt(2)
	v_mfma_f32_32x32x16_bf16 v[50:65], v[236:239], v[244:247], v[50:65]
	s_waitcnt lgkmcnt(1)
	v_mfma_f32_32x32x16_bf16 v[34:49], v[236:239], v[248:251], v[34:49]
	ds_read_b128 v[236:239], v175
	s_waitcnt lgkmcnt(1)
	v_mfma_f32_32x32x16_bf16 v[18:33], v[240:243], v[244:247], v[18:33]
	ds_read_b128 v[244:247], v179
	v_mfma_f32_32x32x16_bf16 v[2:17], v[240:243], v[248:251], v[2:17]
	ds_read_b128 v[248:251], v179 offset:4096
	ds_read_b128 v[240:243], v175 offset:4096
	s_waitcnt lgkmcnt(2)
	v_mfma_f32_32x32x16_bf16 v[50:65], v[236:239], v[244:247], v[50:65]
	s_waitcnt lgkmcnt(1)
	v_mfma_f32_32x32x16_bf16 v[34:49], v[236:239], v[248:251], v[34:49]
	s_waitcnt lgkmcnt(0)
	v_mfma_f32_32x32x16_bf16 v[18:33], v[240:243], v[244:247], v[18:33]
	v_mfma_f32_32x32x16_bf16 v[2:17], v[240:243], v[248:251], v[2:17]
	s_waitcnt vmcnt(0)
	s_barrier
	s_cmp_eq_u32 s7, 7
	s_cbranch_scc1 .Lmgd_skip
	s_add_u32 m0, s14, 0x0
	s_nop 0
	global_load_lds_dwordx4 v160, s[38:39]
	s_add_u32 m0, s14, 0x400
	s_nop 0
	global_load_lds_dwordx4 v161, s[38:39]
	s_add_u32 m0, s14, 0x800
	s_nop 0
	global_load_lds_dwordx4 v162, s[38:39]
	s_add_u32 m0, s14, 0xc00
	s_nop 0
	global_load_lds_dwordx4 v163, s[38:39]
	s_add_u32 m0, s14, 0x4000
	s_nop 0
	global_load_lds_dwordx4 v160, s[4:5]
	s_add_u32 m0, s14, 0x4400
	s_nop 0
	global_load_lds_dwordx4 v161, s[4:5]
	s_add_u32 m0, s14, 0x4800
	s_nop 0
	global_load_lds_dwordx4 v162, s[4:5]
	s_add_u32 m0, s14, 0x4c00
	s_nop 0
	global_load_lds_dwordx4 v163, s[4:5]
	v_add_u32_e32 v160, 0x80, v160
	v_add_u32_e32 v161, 0x80, v161
	v_add_u32_e32 v162, 0x80, v162
	v_add_u32_e32 v163, 0x80, v163
.Lmgd_skip:
	ds_read_b128 v[236:239], v172 offset:32768
	ds_read_b128 v[244:247], v176 offset:32768
	ds_read_b128 v[248:251], v176 offset:36864
	ds_read_b128 v[240:243], v172 offset:36864
	s_waitcnt lgkmcnt(2)
	v_mfma_f32_32x32x16_bf16 v[50:65], v[236:239], v[244:247], v[50:65]
	s_waitcnt lgkmcnt(1)
	v_mfma_f32_32x32x16_bf16 v[34:49], v[236:239], v[248:251], v[34:49]
	ds_read_b128 v[236:239], v173 offset:32768
	s_waitcnt lgkmcnt(1)
	v_mfma_f32_32x32x16_bf16 v[18:33], v[240:243], v[244:247], v[18:33]
	ds_read_b128 v[244:247], v177 offset:32768
	v_mfma_f32_32x32x16_bf16 v[2:17], v[240:243], v[248:251], v[2:17]
	ds_read_b128 v[248:251], v177 offset:36864
	ds_read_b128 v[240:243], v173 offset:36864
	s_waitcnt lgkmcnt(2)
	v_mfma_f32_32x32x16_bf16 v[50:65], v[236:239], v[244:247], v[50:65]
	s_waitcnt lgkmcnt(1)
	v_mfma_f32_32x32x16_bf16 v[34:49], v[236:239], v[248:251], v[34:49]
	ds_read_b128 v[236:239], v174 offset:32768
	s_waitcnt lgkmcnt(1)
	v_mfma_f32_32x32x16_bf16 v[18:33], v[240:243], v[244:247], v[18:33]
	ds_read_b128 v[244:247], v178 offset:32768
	v_mfma_f32_32x32x16_bf16 v[2:17], v[240:243], v[248:251], v[2:17]
	ds_read_b128 v[248:251], v178 offset:36864
	ds_read_b128 v[240:243], v174 offset:36864
	s_waitcnt lgkmcnt(2)
	v_mfma_f32_32x32x16_bf16 v[50:65], v[236:239], v[244:247], v[50:65]
	s_waitcnt lgkmcnt(1)
	v_mfma_f32_32x32x16_bf16 v[34:49], v[236:239], v[248:251], v[34:49]
	ds_read_b128 v[236:239], v175 offset:32768
	s_waitcnt lgkmcnt(1)
	v_mfma_f32_32x32x16_bf16 v[18:33], v[240:243], v[244:247], v[18:33]
	ds_read_b128 v[244:247], v179 offset:32768
	v_mfma_f32_32x32x16_bf16 v[2:17], v[240:243], v[248:251], v[2:17]
	ds_read_b128 v[248:251], v179 offset:36864
	ds_read_b128 v[240:243], v175 offset:36864
	s_waitcnt lgkmcnt(2)
	v_mfma_f32_32x32x16_bf16 v[50:65], v[236:239], v[244:247], v[50:65]
	s_waitcnt lgkmcnt(1)
	v_mfma_f32_32x32x16_bf16 v[34:49], v[236:239], v[248:251], v[34:49]
	s_waitcnt lgkmcnt(0)
	v_mfma_f32_32x32x16_bf16 v[18:33], v[240:243], v[244:247], v[18:33]
	v_mfma_f32_32x32x16_bf16 v[2:17], v[240:243], v[248:251], v[2:17]
	s_waitcnt vmcnt(0)
	s_add_i32 s7, s7, 1
	s_cmp_lg_u32 s7, 8
	s_cbranch_scc1 .Lmgd_loop
	s_barrier
	s_nop 15
	s_nop 6
	v_mul_f32_e32 v0, 0xbfb8aa3b, v50
	v_exp_f32_e32 v50, v0
	v_mul_f32_e32 v0, 0xbfb8aa3b, v51
	v_exp_f32_e32 v51, v0
	v_mul_f32_e32 v52, 0xbfb8aa3b, v52
	v_mul_f32_e32 v53, 0xbfb8aa3b, v53
	v_exp_f32_e32 v52, v52
	v_pk_add_f32 v[50:51], v[50:51], 1.0 op_sel_hi:[1,0]
	v_exp_f32_e32 v53, v53
	v_div_scale_f32 v0, s[4:5], v51, v51, 1.0
	v_rcp_f32_e32 v156, v0
	v_div_scale_f32 v158, vcc, 1.0, v51, 1.0
	v_pk_add_f32 v[52:53], v[52:53], 1.0 op_sel_hi:[1,0]
	v_fma_f32 v159, -v0, v156, 1.0
	v_fmac_f32_e32 v156, v159, v156
	v_mul_f32_e32 v159, v158, v156
	v_fma_f32 v160, -v0, v159, v158
	v_fmac_f32_e32 v159, v160, v156
	v_fma_f32 v0, -v0, v159, v158
	v_div_scale_f32 v158, s[4:5], v50, v50, 1.0
	v_rcp_f32_e32 v160, v158
	v_div_fmas_f32 v0, v0, v156, v159
	v_div_fixup_f32 v0, v0, v51, 1.0
	v_mul_f32_e32 v34, 0xbfb8aa3b, v34
	v_fma_f32 v51, -v158, v160, 1.0
	v_fmac_f32_e32 v160, v51, v160
	v_div_scale_f32 v51, vcc, 1.0, v50, 1.0
	v_mul_f32_e32 v156, v51, v160
	v_fma_f32 v159, -v158, v156, v51
	v_fmac_f32_e32 v156, v159, v160
	v_fma_f32 v51, -v158, v156, v51
	v_div_scale_f32 v158, s[4:5], v53, v53, 1.0
	v_rcp_f32_e32 v159, v158
	v_div_fmas_f32 v51, v51, v160, v156
	v_div_fixup_f32 v50, v51, v50, 1.0
	v_cvt_pk_bf16_f32 v0, v50, v0
	v_fma_f32 v50, -v158, v159, 1.0
	v_fmac_f32_e32 v159, v50, v159
	v_div_scale_f32 v50, vcc, 1.0, v53, 1.0
	v_mul_f32_e32 v51, v50, v159
	v_fma_f32 v156, -v158, v51, v50
	v_fmac_f32_e32 v51, v156, v159
	v_div_scale_f32 v156, s[4:5], v52, v52, 1.0
	v_fma_f32 v50, -v158, v51, v50
	v_rcp_f32_e32 v158, v156
	v_div_fmas_f32 v50, v50, v159, v51
	v_div_fixup_f32 v53, v50, v53, 1.0
	v_div_scale_f32 v159, vcc, 1.0, v52, 1.0
	v_fma_f32 v50, -v156, v158, 1.0
	v_fmac_f32_e32 v158, v50, v158
	v_mul_f32_e32 v160, v159, v158
	v_fma_f32 v50, -v156, v160, v159
	v_fmac_f32_e32 v160, v50, v158
	v_mul_f32_e32 v50, 0xbfb8aa3b, v54
	v_mul_f32_e32 v51, 0xbfb8aa3b, v55
	v_exp_f32_e32 v50, v50
	v_exp_f32_e32 v51, v51
	v_fma_f32 v54, -v156, v160, v159
	v_div_fmas_f32 v54, v54, v158, v160
	v_div_fixup_f32 v52, v54, v52, 1.0
	v_pk_add_f32 v[50:51], v[50:51], 1.0 op_sel_hi:[1,0]
	v_cvt_pk_bf16_f32 v52, v52, v53
	v_div_scale_f32 v55, s[4:5], v51, v51, 1.0
	v_rcp_f32_e32 v156, v55
	ds_write2st64_b32 v131, v0, v52 offset0:144 offset1:148
	v_div_scale_f32 v54, s[4:5], v50, v50, 1.0
	v_fma_f32 v0, -v55, v156, 1.0
	v_fmac_f32_e32 v156, v0, v156
	v_div_scale_f32 v0, vcc, 1.0, v51, 1.0
	v_mul_f32_e32 v52, v0, v156
	v_fma_f32 v53, -v55, v52, v0
	v_fmac_f32_e32 v52, v53, v156
	v_fma_f32 v0, -v55, v52, v0
	v_rcp_f32_e32 v55, v54
	v_div_fmas_f32 v0, v0, v156, v52
	v_mul_f32_e32 v52, 0xbfb8aa3b, v56
	v_mul_f32_e32 v53, 0xbfb8aa3b, v57
	v_div_fixup_f32 v0, v0, v51, 1.0
	v_fma_f32 v51, -v54, v55, 1.0
	v_exp_f32_e32 v52, v52
	v_exp_f32_e32 v53, v53
	v_fmac_f32_e32 v55, v51, v55
	v_div_scale_f32 v51, vcc, 1.0, v50, 1.0
	v_mul_f32_e32 v156, v51, v55
	v_fma_f32 v56, -v54, v156, v51
	v_fmac_f32_e32 v156, v56, v55
	v_pk_add_f32 v[52:53], v[52:53], 1.0 op_sel_hi:[1,0]
	v_fma_f32 v51, -v54, v156, v51
	v_div_scale_f32 v54, s[4:5], v53, v53, 1.0
	v_rcp_f32_e32 v56, v54
	v_div_fmas_f32 v51, v51, v55, v156
	v_div_fixup_f32 v50, v51, v50, 1.0
	v_cvt_pk_bf16_f32 v0, v50, v0
	v_fma_f32 v50, -v54, v56, 1.0
	v_fmac_f32_e32 v56, v50, v56
	v_div_scale_f32 v50, vcc, 1.0, v53, 1.0
	v_mul_f32_e32 v51, v50, v56
	v_fma_f32 v55, -v54, v51, v50
	v_fmac_f32_e32 v51, v55, v56
	v_fma_f32 v50, -v54, v51, v50
	v_div_scale_f32 v54, s[4:5], v52, v52, 1.0
	v_rcp_f32_e32 v55, v54
	v_div_fmas_f32 v50, v50, v56, v51
	v_div_fixup_f32 v53, v50, v53, 1.0
	v_div_scale_f32 v56, vcc, 1.0, v52, 1.0
	v_fma_f32 v50, -v54, v55, 1.0
	v_fmac_f32_e32 v55, v50, v55
	v_mul_f32_e32 v57, v56, v55
	v_fma_f32 v50, -v54, v57, v56
	v_fmac_f32_e32 v57, v50, v55
	v_mul_f32_e32 v50, 0xbfb8aa3b, v58
	v_mul_f32_e32 v51, 0xbfb8aa3b, v59
	v_exp_f32_e32 v50, v50
	v_exp_f32_e32 v51, v51
	v_fma_f32 v54, -v54, v57, v56
	v_div_fmas_f32 v54, v54, v55, v57
	v_div_fixup_f32 v52, v54, v52, 1.0
	v_pk_add_f32 v[50:51], v[50:51], 1.0 op_sel_hi:[1,0]
	v_cvt_pk_bf16_f32 v52, v52, v53
	v_div_scale_f32 v55, s[4:5], v51, v51, 1.0
	v_rcp_f32_e32 v56, v55
	ds_write2st64_b32 v131, v0, v52 offset0:152 offset1:156
	v_div_scale_f32 v54, s[4:5], v50, v50, 1.0
	v_fma_f32 v0, -v55, v56, 1.0
	v_fmac_f32_e32 v56, v0, v56
	v_div_scale_f32 v0, vcc, 1.0, v51, 1.0
	v_mul_f32_e32 v52, v0, v56
	v_fma_f32 v53, -v55, v52, v0
	v_fmac_f32_e32 v52, v53, v56
	v_fma_f32 v0, -v55, v52, v0
	v_rcp_f32_e32 v55, v54
	v_div_fmas_f32 v0, v0, v56, v52
	v_mul_f32_e32 v52, 0xbfb8aa3b, v60
	v_mul_f32_e32 v53, 0xbfb8aa3b, v61
	v_div_fixup_f32 v0, v0, v51, 1.0
	v_fma_f32 v51, -v54, v55, 1.0
	v_exp_f32_e32 v52, v52
	v_exp_f32_e32 v53, v53
	v_fmac_f32_e32 v55, v51, v55
	v_div_scale_f32 v51, vcc, 1.0, v50, 1.0
	v_mul_f32_e32 v56, v51, v55
	v_fma_f32 v57, -v54, v56, v51
	v_fmac_f32_e32 v56, v57, v55
	v_pk_add_f32 v[52:53], v[52:53], 1.0 op_sel_hi:[1,0]
	v_fma_f32 v51, -v54, v56, v51
	v_div_scale_f32 v54, s[4:5], v53, v53, 1.0
	v_rcp_f32_e32 v57, v54
	v_div_fmas_f32 v51, v51, v55, v56
	v_div_fixup_f32 v50, v51, v50, 1.0
	v_cvt_pk_bf16_f32 v0, v50, v0
	v_fma_f32 v50, -v54, v57, 1.0
	v_fmac_f32_e32 v57, v50, v57
	v_div_scale_f32 v50, vcc, 1.0, v53, 1.0
	v_mul_f32_e32 v51, v50, v57
	v_fma_f32 v55, -v54, v51, v50
	v_fmac_f32_e32 v51, v55, v57
	v_fma_f32 v50, -v54, v51, v50
	v_div_scale_f32 v54, s[4:5], v52, v52, 1.0
	v_rcp_f32_e32 v55, v54
	v_div_fmas_f32 v50, v50, v57, v51
	v_div_fixup_f32 v53, v50, v53, 1.0
	v_div_scale_f32 v56, vcc, 1.0, v52, 1.0
	v_fma_f32 v50, -v54, v55, 1.0
	v_fmac_f32_e32 v55, v50, v55
	v_mul_f32_e32 v57, v56, v55
	v_fma_f32 v50, -v54, v57, v56
	v_fmac_f32_e32 v57, v50, v55
	v_mul_f32_e32 v50, 0xbfb8aa3b, v62
	v_mul_f32_e32 v51, 0xbfb8aa3b, v63
	v_exp_f32_e32 v50, v50
	v_exp_f32_e32 v51, v51
	v_fma_f32 v54, -v54, v57, v56
	v_div_fmas_f32 v54, v54, v55, v57
	v_div_fixup_f32 v52, v54, v52, 1.0
	v_pk_add_f32 v[50:51], v[50:51], 1.0 op_sel_hi:[1,0]
	v_cvt_pk_bf16_f32 v52, v52, v53
	v_div_scale_f32 v55, s[4:5], v51, v51, 1.0
	v_rcp_f32_e32 v56, v55
	ds_write2st64_b32 v131, v0, v52 offset0:160 offset1:164
	v_div_scale_f32 v54, s[4:5], v50, v50, 1.0
	v_fma_f32 v0, -v55, v56, 1.0
	v_fmac_f32_e32 v56, v0, v56
	v_div_scale_f32 v0, vcc, 1.0, v51, 1.0
	v_mul_f32_e32 v52, v0, v56
	v_fma_f32 v53, -v55, v52, v0
	v_fmac_f32_e32 v52, v53, v56
	v_fma_f32 v0, -v55, v52, v0
	v_rcp_f32_e32 v55, v54
	v_div_fmas_f32 v0, v0, v56, v52
	v_mul_f32_e32 v52, 0xbfb8aa3b, v64
	v_mul_f32_e32 v53, 0xbfb8aa3b, v65
	v_div_fixup_f32 v0, v0, v51, 1.0
	v_fma_f32 v51, -v54, v55, 1.0
	v_exp_f32_e32 v52, v52
	v_exp_f32_e32 v53, v53
	v_fmac_f32_e32 v55, v51, v55
	v_div_scale_f32 v51, vcc, 1.0, v50, 1.0
	v_mul_f32_e32 v56, v51, v55
	v_fma_f32 v57, -v54, v56, v51
	v_fmac_f32_e32 v56, v57, v55
	v_pk_add_f32 v[52:53], v[52:53], 1.0 op_sel_hi:[1,0]
	v_fma_f32 v51, -v54, v56, v51
	v_div_scale_f32 v54, s[4:5], v53, v53, 1.0
	v_rcp_f32_e32 v57, v54
	v_div_fmas_f32 v51, v51, v55, v56
	v_div_fixup_f32 v50, v51, v50, 1.0
	v_cvt_pk_bf16_f32 v0, v50, v0
	v_fma_f32 v50, -v54, v57, 1.0
	v_fmac_f32_e32 v57, v50, v57
	v_div_scale_f32 v50, vcc, 1.0, v53, 1.0
	v_mul_f32_e32 v51, v50, v57
	v_fma_f32 v55, -v54, v51, v50
	v_fmac_f32_e32 v51, v55, v57
	v_fma_f32 v50, -v54, v51, v50
	v_div_scale_f32 v54, s[4:5], v52, v52, 1.0
	v_rcp_f32_e32 v55, v54
	v_div_fmas_f32 v50, v50, v57, v51
	v_mul_f32_e32 v35, 0xbfb8aa3b, v35
	v_exp_f32_e32 v34, v34
	v_fma_f32 v51, -v54, v55, 1.0
	v_fmac_f32_e32 v55, v51, v55
	v_div_scale_f32 v51, vcc, 1.0, v52, 1.0
	v_exp_f32_e32 v35, v35
	v_div_fixup_f32 v50, v50, v53, 1.0
	v_mul_f32_e32 v53, v51, v55
	v_fma_f32 v56, -v54, v53, v51
	v_fmac_f32_e32 v53, v56, v55
	v_fma_f32 v51, -v54, v53, v51
	v_pk_add_f32 v[34:35], v[34:35], 1.0 op_sel_hi:[1,0]
	v_div_fmas_f32 v51, v51, v55, v53
	v_div_scale_f32 v53, s[4:5], v35, v35, 1.0
	v_rcp_f32_e32 v54, v53
	v_div_fixup_f32 v51, v51, v52, 1.0
	v_cvt_pk_bf16_f32 v50, v51, v50
	ds_write2st64_b32 v131, v0, v50 offset0:168 offset1:172
	v_fma_f32 v0, -v53, v54, 1.0
	v_fmac_f32_e32 v54, v0, v54
	v_div_scale_f32 v0, vcc, 1.0, v35, 1.0
	v_mul_f32_e32 v50, v0, v54
	v_fma_f32 v51, -v53, v50, v0
	v_fmac_f32_e32 v50, v51, v54
	v_div_scale_f32 v51, s[4:5], v34, v34, 1.0
	v_rcp_f32_e32 v52, v51
	v_fma_f32 v0, -v53, v50, v0
	v_div_fmas_f32 v0, v0, v54, v50
	v_mul_f32_e32 v36, 0xbfb8aa3b, v36
	v_mul_f32_e32 v37, 0xbfb8aa3b, v37
	v_div_fixup_f32 v0, v0, v35, 1.0
	v_fma_f32 v35, -v51, v52, 1.0
	v_exp_f32_e32 v36, v36
	v_exp_f32_e32 v37, v37
	v_fmac_f32_e32 v52, v35, v52
	v_div_scale_f32 v35, vcc, 1.0, v34, 1.0
	v_mul_f32_e32 v50, v35, v52
	v_fma_f32 v53, -v51, v50, v35
	v_fmac_f32_e32 v50, v53, v52
	v_pk_add_f32 v[36:37], v[36:37], 1.0 op_sel_hi:[1,0]
	v_fma_f32 v35, -v51, v50, v35
	v_div_scale_f32 v51, s[4:5], v37, v37, 1.0
	v_rcp_f32_e32 v53, v51
	v_div_fmas_f32 v35, v35, v52, v50
	v_div_fixup_f32 v34, v35, v34, 1.0
	v_cvt_pk_bf16_f32 v0, v34, v0
	v_fma_f32 v34, -v51, v53, 1.0
	v_fmac_f32_e32 v53, v34, v53
	v_div_scale_f32 v34, vcc, 1.0, v37, 1.0
	v_mul_f32_e32 v35, v34, v53
	v_fma_f32 v50, -v51, v35, v34
	v_fmac_f32_e32 v35, v50, v53
	v_div_scale_f32 v50, s[4:5], v36, v36, 1.0
	v_fma_f32 v34, -v51, v35, v34
	v_rcp_f32_e32 v51, v50
	v_div_fmas_f32 v34, v34, v53, v35
	v_div_fixup_f32 v37, v34, v37, 1.0
	v_div_scale_f32 v52, vcc, 1.0, v36, 1.0
	v_fma_f32 v34, -v50, v51, 1.0
	v_fmac_f32_e32 v51, v34, v51
	v_mul_f32_e32 v53, v52, v51
	v_fma_f32 v34, -v50, v53, v52
	v_fmac_f32_e32 v53, v34, v51
	v_mul_f32_e32 v34, 0xbfb8aa3b, v38
	v_mul_f32_e32 v35, 0xbfb8aa3b, v39
	v_exp_f32_e32 v34, v34
	v_exp_f32_e32 v35, v35
	v_fma_f32 v38, -v50, v53, v52
	v_div_fmas_f32 v38, v38, v51, v53
	v_div_fixup_f32 v36, v38, v36, 1.0
	v_pk_add_f32 v[34:35], v[34:35], 1.0 op_sel_hi:[1,0]
	v_cvt_pk_bf16_f32 v36, v36, v37
	v_div_scale_f32 v39, s[4:5], v35, v35, 1.0
	v_rcp_f32_e32 v50, v39
	ds_write2st64_b32 v131, v0, v36 offset0:176 offset1:180
	v_div_scale_f32 v38, s[4:5], v34, v34, 1.0
	v_fma_f32 v0, -v39, v50, 1.0
	v_fmac_f32_e32 v50, v0, v50
	v_div_scale_f32 v0, vcc, 1.0, v35, 1.0
	v_mul_f32_e32 v36, v0, v50
	v_fma_f32 v37, -v39, v36, v0
	v_fmac_f32_e32 v36, v37, v50
	v_fma_f32 v0, -v39, v36, v0
	v_rcp_f32_e32 v39, v38
	v_div_fmas_f32 v0, v0, v50, v36
	v_mul_f32_e32 v36, 0xbfb8aa3b, v40
	v_mul_f32_e32 v37, 0xbfb8aa3b, v41
	v_div_fixup_f32 v0, v0, v35, 1.0
	v_fma_f32 v35, -v38, v39, 1.0
	v_exp_f32_e32 v36, v36
	v_exp_f32_e32 v37, v37
	v_fmac_f32_e32 v39, v35, v39
	v_div_scale_f32 v35, vcc, 1.0, v34, 1.0
	v_mul_f32_e32 v50, v35, v39
	v_fma_f32 v40, -v38, v50, v35
	v_fmac_f32_e32 v50, v40, v39
	v_pk_add_f32 v[36:37], v[36:37], 1.0 op_sel_hi:[1,0]
	v_fma_f32 v35, -v38, v50, v35
	v_div_scale_f32 v38, s[4:5], v37, v37, 1.0
	v_rcp_f32_e32 v40, v38
	v_div_fmas_f32 v35, v35, v39, v50
	v_div_fixup_f32 v34, v35, v34, 1.0
	v_cvt_pk_bf16_f32 v0, v34, v0
	v_fma_f32 v34, -v38, v40, 1.0
	v_fmac_f32_e32 v40, v34, v40
	v_div_scale_f32 v34, vcc, 1.0, v37, 1.0
	v_mul_f32_e32 v35, v34, v40
	v_fma_f32 v39, -v38, v35, v34
	v_fmac_f32_e32 v35, v39, v40
	v_fma_f32 v34, -v38, v35, v34
	v_div_scale_f32 v38, s[4:5], v36, v36, 1.0
	v_rcp_f32_e32 v39, v38
	v_div_fmas_f32 v34, v34, v40, v35
	v_div_fixup_f32 v37, v34, v37, 1.0
	v_div_scale_f32 v40, vcc, 1.0, v36, 1.0
	v_fma_f32 v34, -v38, v39, 1.0
	v_fmac_f32_e32 v39, v34, v39
	v_mul_f32_e32 v41, v40, v39
	v_fma_f32 v34, -v38, v41, v40
	v_fmac_f32_e32 v41, v34, v39
	v_mul_f32_e32 v34, 0xbfb8aa3b, v42
	v_mul_f32_e32 v35, 0xbfb8aa3b, v43
	v_exp_f32_e32 v34, v34
	v_exp_f32_e32 v35, v35
	v_fma_f32 v38, -v38, v41, v40
	v_div_fmas_f32 v38, v38, v39, v41
	v_div_fixup_f32 v36, v38, v36, 1.0
	v_pk_add_f32 v[34:35], v[34:35], 1.0 op_sel_hi:[1,0]
	v_cvt_pk_bf16_f32 v36, v36, v37
	v_div_scale_f32 v39, s[4:5], v35, v35, 1.0
	v_rcp_f32_e32 v40, v39
	ds_write2st64_b32 v131, v0, v36 offset0:184 offset1:188
	v_div_scale_f32 v38, s[4:5], v34, v34, 1.0
	v_fma_f32 v0, -v39, v40, 1.0
	v_fmac_f32_e32 v40, v0, v40
	v_div_scale_f32 v0, vcc, 1.0, v35, 1.0
	v_mul_f32_e32 v36, v0, v40
	v_fma_f32 v37, -v39, v36, v0
	v_fmac_f32_e32 v36, v37, v40
	v_fma_f32 v0, -v39, v36, v0
	v_rcp_f32_e32 v39, v38
	v_div_fmas_f32 v0, v0, v40, v36
	v_mul_f32_e32 v36, 0xbfb8aa3b, v44
	v_mul_f32_e32 v37, 0xbfb8aa3b, v45
	v_div_fixup_f32 v0, v0, v35, 1.0
	v_fma_f32 v35, -v38, v39, 1.0
	v_exp_f32_e32 v36, v36
	v_exp_f32_e32 v37, v37
	v_fmac_f32_e32 v39, v35, v39
	v_div_scale_f32 v35, vcc, 1.0, v34, 1.0
	v_mul_f32_e32 v40, v35, v39
	v_fma_f32 v41, -v38, v40, v35
	v_fmac_f32_e32 v40, v41, v39
	v_pk_add_f32 v[36:37], v[36:37], 1.0 op_sel_hi:[1,0]
	v_fma_f32 v35, -v38, v40, v35
	v_div_scale_f32 v38, s[4:5], v37, v37, 1.0
	v_rcp_f32_e32 v41, v38
	v_div_fmas_f32 v35, v35, v39, v40
	v_div_fixup_f32 v34, v35, v34, 1.0
	v_cvt_pk_bf16_f32 v0, v34, v0
	v_fma_f32 v34, -v38, v41, 1.0
	v_fmac_f32_e32 v41, v34, v41
	v_div_scale_f32 v34, vcc, 1.0, v37, 1.0
	v_mul_f32_e32 v35, v34, v41
	v_fma_f32 v39, -v38, v35, v34
	v_fmac_f32_e32 v35, v39, v41
	v_fma_f32 v34, -v38, v35, v34
	v_div_scale_f32 v38, s[4:5], v36, v36, 1.0
	v_rcp_f32_e32 v39, v38
	v_div_fmas_f32 v34, v34, v41, v35
	v_div_fixup_f32 v37, v34, v37, 1.0
	v_div_scale_f32 v40, vcc, 1.0, v36, 1.0
	v_fma_f32 v34, -v38, v39, 1.0
	v_fmac_f32_e32 v39, v34, v39
	v_mul_f32_e32 v41, v40, v39
	v_fma_f32 v34, -v38, v41, v40
	v_fmac_f32_e32 v41, v34, v39
	v_mul_f32_e32 v34, 0xbfb8aa3b, v46
	v_mul_f32_e32 v35, 0xbfb8aa3b, v47
	v_exp_f32_e32 v34, v34
	v_exp_f32_e32 v35, v35
	v_fma_f32 v38, -v38, v41, v40
	v_div_fmas_f32 v38, v38, v39, v41
	v_div_fixup_f32 v36, v38, v36, 1.0
	v_pk_add_f32 v[34:35], v[34:35], 1.0 op_sel_hi:[1,0]
	v_cvt_pk_bf16_f32 v36, v36, v37
	v_div_scale_f32 v39, s[4:5], v35, v35, 1.0
	v_rcp_f32_e32 v40, v39
	ds_write2st64_b32 v131, v0, v36 offset0:192 offset1:196
	v_div_scale_f32 v38, s[4:5], v34, v34, 1.0
	v_fma_f32 v0, -v39, v40, 1.0
	v_fmac_f32_e32 v40, v0, v40
	v_div_scale_f32 v0, vcc, 1.0, v35, 1.0
	v_mul_f32_e32 v36, v0, v40
	v_fma_f32 v37, -v39, v36, v0
	v_fmac_f32_e32 v36, v37, v40
	v_fma_f32 v0, -v39, v36, v0
	v_rcp_f32_e32 v39, v38
	v_div_fmas_f32 v0, v0, v40, v36
	v_mul_f32_e32 v36, 0xbfb8aa3b, v48
	v_mul_f32_e32 v37, 0xbfb8aa3b, v49
	v_div_fixup_f32 v0, v0, v35, 1.0
	v_fma_f32 v35, -v38, v39, 1.0
	v_exp_f32_e32 v36, v36
	v_exp_f32_e32 v37, v37
	v_fmac_f32_e32 v39, v35, v39
	v_div_scale_f32 v35, vcc, 1.0, v34, 1.0
	v_mul_f32_e32 v40, v35, v39
	v_fma_f32 v41, -v38, v40, v35
	v_fmac_f32_e32 v40, v41, v39
	v_pk_add_f32 v[36:37], v[36:37], 1.0 op_sel_hi:[1,0]
	v_fma_f32 v35, -v38, v40, v35
	v_div_scale_f32 v38, s[4:5], v37, v37, 1.0
	v_rcp_f32_e32 v41, v38
	v_div_fmas_f32 v35, v35, v39, v40
	v_div_fixup_f32 v34, v35, v34, 1.0
	v_cvt_pk_bf16_f32 v0, v34, v0
	v_fma_f32 v34, -v38, v41, 1.0
	v_fmac_f32_e32 v41, v34, v41
	v_div_scale_f32 v34, vcc, 1.0, v37, 1.0
	v_mul_f32_e32 v35, v34, v41
	v_fma_f32 v39, -v38, v35, v34
	v_fmac_f32_e32 v35, v39, v41
	v_fma_f32 v34, -v38, v35, v34
	v_div_scale_f32 v38, s[4:5], v36, v36, 1.0
	v_rcp_f32_e32 v39, v38
	v_div_fmas_f32 v34, v34, v41, v35
	v_mul_f32_e32 v18, 0xbfb8aa3b, v18
	v_mul_f32_e32 v19, 0xbfb8aa3b, v19
	v_fma_f32 v35, -v38, v39, 1.0
	v_fmac_f32_e32 v39, v35, v39
	v_div_scale_f32 v35, vcc, 1.0, v36, 1.0
	v_exp_f32_e32 v18, v18
	v_exp_f32_e32 v19, v19
	v_div_fixup_f32 v34, v34, v37, 1.0
	v_mul_f32_e32 v37, v35, v39
	v_fma_f32 v40, -v38, v37, v35
	v_fmac_f32_e32 v37, v40, v39
	v_fma_f32 v35, -v38, v37, v35
	v_pk_add_f32 v[18:19], v[18:19], 1.0 op_sel_hi:[1,0]
	v_div_fmas_f32 v35, v35, v39, v37
	v_div_scale_f32 v37, s[4:5], v19, v19, 1.0
	v_rcp_f32_e32 v38, v37
	v_div_fixup_f32 v35, v35, v36, 1.0
	v_cvt_pk_bf16_f32 v34, v35, v34
	ds_write2st64_b32 v131, v0, v34 offset0:200 offset1:204
	v_fma_f32 v0, -v37, v38, 1.0
	v_fmac_f32_e32 v38, v0, v38
	v_div_scale_f32 v0, vcc, 1.0, v19, 1.0
	v_mul_f32_e32 v34, v0, v38
	v_fma_f32 v35, -v37, v34, v0
	v_fmac_f32_e32 v34, v35, v38
	v_div_scale_f32 v35, s[4:5], v18, v18, 1.0
	v_rcp_f32_e32 v36, v35
	v_fma_f32 v0, -v37, v34, v0
	v_div_fmas_f32 v0, v0, v38, v34
	v_mul_f32_e32 v20, 0xbfb8aa3b, v20
	v_mul_f32_e32 v21, 0xbfb8aa3b, v21
	v_div_fixup_f32 v0, v0, v19, 1.0
	v_fma_f32 v19, -v35, v36, 1.0
	v_exp_f32_e32 v20, v20
	v_exp_f32_e32 v21, v21
	v_fmac_f32_e32 v36, v19, v36
	v_div_scale_f32 v19, vcc, 1.0, v18, 1.0
	v_mul_f32_e32 v34, v19, v36
	v_fma_f32 v37, -v35, v34, v19
	v_fmac_f32_e32 v34, v37, v36
	v_pk_add_f32 v[20:21], v[20:21], 1.0 op_sel_hi:[1,0]
	v_fma_f32 v19, -v35, v34, v19
	v_div_scale_f32 v35, s[4:5], v21, v21, 1.0
	v_rcp_f32_e32 v37, v35
	v_div_fmas_f32 v19, v19, v36, v34
	v_div_fixup_f32 v18, v19, v18, 1.0
	v_cvt_pk_bf16_f32 v0, v18, v0
	v_fma_f32 v18, -v35, v37, 1.0
	v_fmac_f32_e32 v37, v18, v37
	v_div_scale_f32 v18, vcc, 1.0, v21, 1.0
	v_mul_f32_e32 v19, v18, v37
	v_fma_f32 v34, -v35, v19, v18
	v_fmac_f32_e32 v19, v34, v37
	v_div_scale_f32 v34, s[4:5], v20, v20, 1.0
	v_fma_f32 v18, -v35, v19, v18
	v_rcp_f32_e32 v35, v34
	v_div_fmas_f32 v18, v18, v37, v19
	v_div_fixup_f32 v21, v18, v21, 1.0
	v_div_scale_f32 v36, vcc, 1.0, v20, 1.0
	v_fma_f32 v18, -v34, v35, 1.0
	v_fmac_f32_e32 v35, v18, v35
	v_mul_f32_e32 v37, v36, v35
	v_fma_f32 v18, -v34, v37, v36
	v_fmac_f32_e32 v37, v18, v35
	v_mul_f32_e32 v18, 0xbfb8aa3b, v22
	v_mul_f32_e32 v19, 0xbfb8aa3b, v23
	v_exp_f32_e32 v18, v18
	v_exp_f32_e32 v19, v19
	v_fma_f32 v22, -v34, v37, v36
	v_div_fmas_f32 v22, v22, v35, v37
	v_div_fixup_f32 v20, v22, v20, 1.0
	v_pk_add_f32 v[18:19], v[18:19], 1.0 op_sel_hi:[1,0]
	v_cvt_pk_bf16_f32 v20, v20, v21
	v_div_scale_f32 v23, s[4:5], v19, v19, 1.0
	v_rcp_f32_e32 v34, v23
	ds_write2st64_b32 v131, v0, v20 offset0:208 offset1:212
	v_div_scale_f32 v22, s[4:5], v18, v18, 1.0
	v_fma_f32 v0, -v23, v34, 1.0
	v_fmac_f32_e32 v34, v0, v34
	v_div_scale_f32 v0, vcc, 1.0, v19, 1.0
	v_mul_f32_e32 v20, v0, v34
	v_fma_f32 v21, -v23, v20, v0
	v_fmac_f32_e32 v20, v21, v34
	v_fma_f32 v0, -v23, v20, v0
	v_rcp_f32_e32 v23, v22
	v_div_fmas_f32 v0, v0, v34, v20
	v_mul_f32_e32 v20, 0xbfb8aa3b, v24
	v_mul_f32_e32 v21, 0xbfb8aa3b, v25
	v_div_fixup_f32 v0, v0, v19, 1.0
	v_fma_f32 v19, -v22, v23, 1.0
	v_exp_f32_e32 v20, v20
	v_exp_f32_e32 v21, v21
	v_fmac_f32_e32 v23, v19, v23
	v_div_scale_f32 v19, vcc, 1.0, v18, 1.0
	v_mul_f32_e32 v34, v19, v23
	v_fma_f32 v24, -v22, v34, v19
	v_fmac_f32_e32 v34, v24, v23
	v_pk_add_f32 v[20:21], v[20:21], 1.0 op_sel_hi:[1,0]
	v_fma_f32 v19, -v22, v34, v19
	v_div_scale_f32 v22, s[4:5], v21, v21, 1.0
	v_rcp_f32_e32 v24, v22
	v_div_fmas_f32 v19, v19, v23, v34
	v_div_fixup_f32 v18, v19, v18, 1.0
	v_cvt_pk_bf16_f32 v0, v18, v0
	v_fma_f32 v18, -v22, v24, 1.0
	v_fmac_f32_e32 v24, v18, v24
	v_div_scale_f32 v18, vcc, 1.0, v21, 1.0
	v_mul_f32_e32 v19, v18, v24
	v_fma_f32 v23, -v22, v19, v18
	v_fmac_f32_e32 v19, v23, v24
	v_fma_f32 v18, -v22, v19, v18
	v_div_scale_f32 v22, s[4:5], v20, v20, 1.0
	v_rcp_f32_e32 v23, v22
	v_div_fmas_f32 v18, v18, v24, v19
	v_div_fixup_f32 v21, v18, v21, 1.0
	v_div_scale_f32 v24, vcc, 1.0, v20, 1.0
	v_fma_f32 v18, -v22, v23, 1.0
	v_fmac_f32_e32 v23, v18, v23
	v_mul_f32_e32 v25, v24, v23
	v_fma_f32 v18, -v22, v25, v24
	v_fmac_f32_e32 v25, v18, v23
	v_mul_f32_e32 v18, 0xbfb8aa3b, v26
	v_mul_f32_e32 v19, 0xbfb8aa3b, v27
	v_exp_f32_e32 v18, v18
	v_exp_f32_e32 v19, v19
	v_fma_f32 v22, -v22, v25, v24
	v_div_fmas_f32 v22, v22, v23, v25
	v_div_fixup_f32 v20, v22, v20, 1.0
	v_pk_add_f32 v[18:19], v[18:19], 1.0 op_sel_hi:[1,0]
	v_cvt_pk_bf16_f32 v20, v20, v21
	v_div_scale_f32 v23, s[4:5], v19, v19, 1.0
	v_rcp_f32_e32 v24, v23
	ds_write2st64_b32 v131, v0, v20 offset0:216 offset1:220
	v_div_scale_f32 v22, s[4:5], v18, v18, 1.0
	v_fma_f32 v0, -v23, v24, 1.0
	v_fmac_f32_e32 v24, v0, v24
	v_div_scale_f32 v0, vcc, 1.0, v19, 1.0
	v_mul_f32_e32 v20, v0, v24
	v_fma_f32 v21, -v23, v20, v0
	v_fmac_f32_e32 v20, v21, v24
	v_fma_f32 v0, -v23, v20, v0
	v_rcp_f32_e32 v23, v22
	v_div_fmas_f32 v0, v0, v24, v20
	v_mul_f32_e32 v20, 0xbfb8aa3b, v28
	v_mul_f32_e32 v21, 0xbfb8aa3b, v29
	v_div_fixup_f32 v0, v0, v19, 1.0
	v_fma_f32 v19, -v22, v23, 1.0
	v_exp_f32_e32 v20, v20
	v_exp_f32_e32 v21, v21
	v_fmac_f32_e32 v23, v19, v23
	v_div_scale_f32 v19, vcc, 1.0, v18, 1.0
	v_mul_f32_e32 v24, v19, v23
	v_fma_f32 v25, -v22, v24, v19
	v_fmac_f32_e32 v24, v25, v23
	v_pk_add_f32 v[20:21], v[20:21], 1.0 op_sel_hi:[1,0]
	v_fma_f32 v19, -v22, v24, v19
	v_div_scale_f32 v22, s[4:5], v21, v21, 1.0
	v_rcp_f32_e32 v25, v22
	v_div_fmas_f32 v19, v19, v23, v24
	v_div_fixup_f32 v18, v19, v18, 1.0
	v_cvt_pk_bf16_f32 v0, v18, v0
	v_fma_f32 v18, -v22, v25, 1.0
	v_fmac_f32_e32 v25, v18, v25
	v_div_scale_f32 v18, vcc, 1.0, v21, 1.0
	v_mul_f32_e32 v19, v18, v25
	v_fma_f32 v23, -v22, v19, v18
	v_fmac_f32_e32 v19, v23, v25
	v_fma_f32 v18, -v22, v19, v18
	v_div_scale_f32 v22, s[4:5], v20, v20, 1.0
	v_rcp_f32_e32 v23, v22
	v_div_fmas_f32 v18, v18, v25, v19
	v_div_fixup_f32 v21, v18, v21, 1.0
	v_div_scale_f32 v24, vcc, 1.0, v20, 1.0
	v_fma_f32 v18, -v22, v23, 1.0
	v_fmac_f32_e32 v23, v18, v23
	v_mul_f32_e32 v25, v24, v23
	v_fma_f32 v18, -v22, v25, v24
	v_fmac_f32_e32 v25, v18, v23
	v_mul_f32_e32 v18, 0xbfb8aa3b, v30
	v_mul_f32_e32 v19, 0xbfb8aa3b, v31
	v_exp_f32_e32 v18, v18
	v_exp_f32_e32 v19, v19
	v_fma_f32 v22, -v22, v25, v24
	v_div_fmas_f32 v22, v22, v23, v25
	v_div_fixup_f32 v20, v22, v20, 1.0
	v_pk_add_f32 v[18:19], v[18:19], 1.0 op_sel_hi:[1,0]
	v_cvt_pk_bf16_f32 v20, v20, v21
	v_div_scale_f32 v23, s[4:5], v19, v19, 1.0
	v_rcp_f32_e32 v24, v23
	ds_write2st64_b32 v131, v0, v20 offset0:224 offset1:228
	v_div_scale_f32 v22, s[4:5], v18, v18, 1.0
	v_fma_f32 v0, -v23, v24, 1.0
	v_fmac_f32_e32 v24, v0, v24
	v_div_scale_f32 v0, vcc, 1.0, v19, 1.0
	v_mul_f32_e32 v20, v0, v24
	v_fma_f32 v21, -v23, v20, v0
	v_fmac_f32_e32 v20, v21, v24
	v_fma_f32 v0, -v23, v20, v0
	v_rcp_f32_e32 v23, v22
	v_div_fmas_f32 v0, v0, v24, v20
	v_mul_f32_e32 v20, 0xbfb8aa3b, v32
	v_mul_f32_e32 v21, 0xbfb8aa3b, v33
	v_div_fixup_f32 v0, v0, v19, 1.0
	v_fma_f32 v19, -v22, v23, 1.0
	v_exp_f32_e32 v20, v20
	v_exp_f32_e32 v21, v21
	v_fmac_f32_e32 v23, v19, v23
	v_div_scale_f32 v19, vcc, 1.0, v18, 1.0
	v_mul_f32_e32 v24, v19, v23
	v_fma_f32 v25, -v22, v24, v19
	v_fmac_f32_e32 v24, v25, v23
	v_pk_add_f32 v[20:21], v[20:21], 1.0 op_sel_hi:[1,0]
	v_fma_f32 v19, -v22, v24, v19
	v_div_scale_f32 v22, s[4:5], v21, v21, 1.0
	v_rcp_f32_e32 v25, v22
	v_div_fmas_f32 v19, v19, v23, v24
	v_div_fixup_f32 v18, v19, v18, 1.0
	v_cvt_pk_bf16_f32 v0, v18, v0
	v_fma_f32 v18, -v22, v25, 1.0
	v_fmac_f32_e32 v25, v18, v25
	v_div_scale_f32 v18, vcc, 1.0, v21, 1.0
	v_mul_f32_e32 v19, v18, v25
	v_fma_f32 v23, -v22, v19, v18
	v_fmac_f32_e32 v19, v23, v25
	v_fma_f32 v18, -v22, v19, v18
	v_div_scale_f32 v22, s[4:5], v20, v20, 1.0
	v_rcp_f32_e32 v23, v22
	v_div_fmas_f32 v18, v18, v25, v19
	v_mul_f32_e32 v2, 0xbfb8aa3b, v2
	v_mul_f32_e32 v3, 0xbfb8aa3b, v3
	v_fma_f32 v19, -v22, v23, 1.0
	v_fmac_f32_e32 v23, v19, v23
	v_div_scale_f32 v19, vcc, 1.0, v20, 1.0
	v_exp_f32_e32 v2, v2
	v_exp_f32_e32 v3, v3
	v_div_fixup_f32 v18, v18, v21, 1.0
	v_mul_f32_e32 v21, v19, v23
	v_fma_f32 v24, -v22, v21, v19
	v_fmac_f32_e32 v21, v24, v23
	v_fma_f32 v19, -v22, v21, v19
	v_pk_add_f32 v[2:3], v[2:3], 1.0 op_sel_hi:[1,0]
	v_div_fmas_f32 v19, v19, v23, v21
	v_div_scale_f32 v21, s[4:5], v3, v3, 1.0
	v_rcp_f32_e32 v22, v21
	v_div_fixup_f32 v19, v19, v20, 1.0
	v_cvt_pk_bf16_f32 v18, v19, v18
	ds_write2st64_b32 v131, v0, v18 offset0:232 offset1:236
	v_fma_f32 v0, -v21, v22, 1.0
	v_fmac_f32_e32 v22, v0, v22
	v_div_scale_f32 v0, vcc, 1.0, v3, 1.0
	v_mul_f32_e32 v18, v0, v22
	v_fma_f32 v19, -v21, v18, v0
	v_fmac_f32_e32 v18, v19, v22
	v_div_scale_f32 v19, s[4:5], v2, v2, 1.0
	v_rcp_f32_e32 v20, v19
	v_fma_f32 v0, -v21, v18, v0
	v_div_fmas_f32 v0, v0, v22, v18
	v_mul_f32_e32 v4, 0xbfb8aa3b, v4
	v_mul_f32_e32 v5, 0xbfb8aa3b, v5
	v_div_fixup_f32 v0, v0, v3, 1.0
	v_fma_f32 v3, -v19, v20, 1.0
	v_exp_f32_e32 v4, v4
	v_exp_f32_e32 v5, v5
	v_fmac_f32_e32 v20, v3, v20
	v_div_scale_f32 v3, vcc, 1.0, v2, 1.0
	v_mul_f32_e32 v18, v3, v20
	v_fma_f32 v21, -v19, v18, v3
	v_fmac_f32_e32 v18, v21, v20
	v_pk_add_f32 v[4:5], v[4:5], 1.0 op_sel_hi:[1,0]
	v_fma_f32 v3, -v19, v18, v3
	v_div_scale_f32 v19, s[4:5], v5, v5, 1.0
	v_rcp_f32_e32 v21, v19
	v_div_fmas_f32 v3, v3, v20, v18
	v_div_fixup_f32 v2, v3, v2, 1.0
	v_cvt_pk_bf16_f32 v0, v2, v0
	v_fma_f32 v2, -v19, v21, 1.0
	v_fmac_f32_e32 v21, v2, v21
	v_div_scale_f32 v2, vcc, 1.0, v5, 1.0
	v_mul_f32_e32 v3, v2, v21
	v_fma_f32 v18, -v19, v3, v2
	v_fmac_f32_e32 v3, v18, v21
	v_div_scale_f32 v18, s[4:5], v4, v4, 1.0
	v_fma_f32 v2, -v19, v3, v2
	v_rcp_f32_e32 v19, v18
	v_div_fmas_f32 v2, v2, v21, v3
	v_div_fixup_f32 v5, v2, v5, 1.0
	v_div_scale_f32 v20, vcc, 1.0, v4, 1.0
	v_fma_f32 v2, -v18, v19, 1.0
	v_fmac_f32_e32 v19, v2, v19
	v_mul_f32_e32 v21, v20, v19
	v_fma_f32 v2, -v18, v21, v20
	v_fmac_f32_e32 v21, v2, v19
	v_mul_f32_e32 v2, 0xbfb8aa3b, v6
	v_mul_f32_e32 v3, 0xbfb8aa3b, v7
	v_exp_f32_e32 v2, v2
	v_exp_f32_e32 v3, v3
	v_fma_f32 v6, -v18, v21, v20
	v_div_fmas_f32 v6, v6, v19, v21
	v_div_fixup_f32 v4, v6, v4, 1.0
	v_pk_add_f32 v[2:3], v[2:3], 1.0 op_sel_hi:[1,0]
	v_cvt_pk_bf16_f32 v4, v4, v5
	v_div_scale_f32 v7, s[4:5], v3, v3, 1.0
	v_rcp_f32_e32 v18, v7
	ds_write2st64_b32 v131, v0, v4 offset0:240 offset1:244
	v_div_scale_f32 v6, s[4:5], v2, v2, 1.0
	v_fma_f32 v0, -v7, v18, 1.0
	v_fmac_f32_e32 v18, v0, v18
	v_div_scale_f32 v0, vcc, 1.0, v3, 1.0
	v_mul_f32_e32 v4, v0, v18
	v_fma_f32 v5, -v7, v4, v0
	v_fmac_f32_e32 v4, v5, v18
	v_fma_f32 v0, -v7, v4, v0
	v_rcp_f32_e32 v7, v6
	v_div_fmas_f32 v0, v0, v18, v4
	v_mul_f32_e32 v4, 0xbfb8aa3b, v8
	v_mul_f32_e32 v5, 0xbfb8aa3b, v9
	v_div_fixup_f32 v0, v0, v3, 1.0
	v_fma_f32 v3, -v6, v7, 1.0
	v_exp_f32_e32 v4, v4
	v_exp_f32_e32 v5, v5
	v_fmac_f32_e32 v7, v3, v7
	v_div_scale_f32 v3, vcc, 1.0, v2, 1.0
	v_mul_f32_e32 v18, v3, v7
	v_fma_f32 v8, -v6, v18, v3
	v_fmac_f32_e32 v18, v8, v7
	v_pk_add_f32 v[4:5], v[4:5], 1.0 op_sel_hi:[1,0]
	v_fma_f32 v3, -v6, v18, v3
	v_div_scale_f32 v6, s[4:5], v5, v5, 1.0
	v_rcp_f32_e32 v8, v6
	v_div_fmas_f32 v3, v3, v7, v18
	v_div_fixup_f32 v2, v3, v2, 1.0
	v_cvt_pk_bf16_f32 v0, v2, v0
	v_fma_f32 v2, -v6, v8, 1.0
	v_fmac_f32_e32 v8, v2, v8
	v_div_scale_f32 v2, vcc, 1.0, v5, 1.0
	v_mul_f32_e32 v3, v2, v8
	v_fma_f32 v7, -v6, v3, v2
	v_fmac_f32_e32 v3, v7, v8
	v_fma_f32 v2, -v6, v3, v2
	v_div_scale_f32 v6, s[4:5], v4, v4, 1.0
	v_rcp_f32_e32 v7, v6
	v_div_fmas_f32 v2, v2, v8, v3
	v_div_fixup_f32 v5, v2, v5, 1.0
	v_div_scale_f32 v8, vcc, 1.0, v4, 1.0
	v_fma_f32 v2, -v6, v7, 1.0
	v_fmac_f32_e32 v7, v2, v7
	v_mul_f32_e32 v9, v8, v7
	v_fma_f32 v2, -v6, v9, v8
	v_fmac_f32_e32 v9, v2, v7
	v_mul_f32_e32 v2, 0xbfb8aa3b, v10
	v_mul_f32_e32 v3, 0xbfb8aa3b, v11
	v_exp_f32_e32 v2, v2
	v_exp_f32_e32 v3, v3
	v_fma_f32 v6, -v6, v9, v8
	v_div_fmas_f32 v6, v6, v7, v9
	v_div_fixup_f32 v4, v6, v4, 1.0
	v_pk_add_f32 v[2:3], v[2:3], 1.0 op_sel_hi:[1,0]
	v_cvt_pk_bf16_f32 v4, v4, v5
	v_div_scale_f32 v7, s[4:5], v3, v3, 1.0
	v_rcp_f32_e32 v8, v7
	ds_write2st64_b32 v131, v0, v4 offset0:248 offset1:252
	v_div_scale_f32 v6, s[4:5], v2, v2, 1.0
	v_fma_f32 v0, -v7, v8, 1.0
	v_fmac_f32_e32 v8, v0, v8
	v_div_scale_f32 v0, vcc, 1.0, v3, 1.0
	v_mul_f32_e32 v4, v0, v8
	v_fma_f32 v5, -v7, v4, v0
	v_fmac_f32_e32 v4, v5, v8
	v_fma_f32 v0, -v7, v4, v0
	v_rcp_f32_e32 v7, v6
	v_div_fmas_f32 v0, v0, v8, v4
	v_mul_f32_e32 v4, 0xbfb8aa3b, v12
	v_mul_f32_e32 v5, 0xbfb8aa3b, v13
	v_div_fixup_f32 v0, v0, v3, 1.0
	v_fma_f32 v3, -v6, v7, 1.0
	v_exp_f32_e32 v4, v4
	v_exp_f32_e32 v5, v5
	v_fmac_f32_e32 v7, v3, v7
	v_div_scale_f32 v3, vcc, 1.0, v2, 1.0
	v_mul_f32_e32 v8, v3, v7
	v_fma_f32 v9, -v6, v8, v3
	v_fmac_f32_e32 v8, v9, v7
	v_pk_add_f32 v[4:5], v[4:5], 1.0 op_sel_hi:[1,0]
	v_fma_f32 v3, -v6, v8, v3
	v_div_scale_f32 v6, s[4:5], v5, v5, 1.0
	v_rcp_f32_e32 v9, v6
	v_div_fmas_f32 v3, v3, v7, v8
	v_div_fixup_f32 v2, v3, v2, 1.0
	v_cvt_pk_bf16_f32 v0, v2, v0
	v_fma_f32 v2, -v6, v9, 1.0
	v_fmac_f32_e32 v9, v2, v9
	v_div_scale_f32 v2, vcc, 1.0, v5, 1.0
	v_mul_f32_e32 v3, v2, v9
	v_fma_f32 v7, -v6, v3, v2
	v_fmac_f32_e32 v3, v7, v9
	v_fma_f32 v2, -v6, v3, v2
	v_div_scale_f32 v6, s[4:5], v4, v4, 1.0
	v_rcp_f32_e32 v7, v6
	v_div_fmas_f32 v2, v2, v9, v3
	v_div_fixup_f32 v5, v2, v5, 1.0
	v_div_scale_f32 v8, vcc, 1.0, v4, 1.0
	v_fma_f32 v2, -v6, v7, 1.0
	v_fmac_f32_e32 v7, v2, v7
	v_mul_f32_e32 v9, v8, v7
	v_fma_f32 v2, -v6, v9, v8
	v_fmac_f32_e32 v9, v2, v7
	v_mul_f32_e32 v2, 0xbfb8aa3b, v14
	v_mul_f32_e32 v3, 0xbfb8aa3b, v15
	v_exp_f32_e32 v2, v2
	v_exp_f32_e32 v3, v3
	v_fma_f32 v6, -v6, v9, v8
	v_div_fmas_f32 v6, v6, v7, v9
	v_div_fixup_f32 v4, v6, v4, 1.0
	v_pk_add_f32 v[2:3], v[2:3], 1.0 op_sel_hi:[1,0]
	v_cvt_pk_bf16_f32 v4, v4, v5
	v_div_scale_f32 v7, s[4:5], v3, v3, 1.0
	v_rcp_f32_e32 v8, v7
	ds_write2st64_b32 v135, v0, v4 offset0:112 offset1:116
	v_div_scale_f32 v6, s[4:5], v2, v2, 1.0
	v_fma_f32 v0, -v7, v8, 1.0
	v_fmac_f32_e32 v8, v0, v8
	v_div_scale_f32 v0, vcc, 1.0, v3, 1.0
	v_mul_f32_e32 v4, v0, v8
	v_fma_f32 v5, -v7, v4, v0
	v_fmac_f32_e32 v4, v5, v8
	v_fma_f32 v0, -v7, v4, v0
	v_rcp_f32_e32 v7, v6
	v_div_fmas_f32 v0, v0, v8, v4
	v_mul_f32_e32 v4, 0xbfb8aa3b, v16
	v_mul_f32_e32 v5, 0xbfb8aa3b, v17
	v_div_fixup_f32 v0, v0, v3, 1.0
	v_fma_f32 v3, -v6, v7, 1.0
	v_exp_f32_e32 v4, v4
	v_exp_f32_e32 v5, v5
	v_fmac_f32_e32 v7, v3, v7
	v_div_scale_f32 v3, vcc, 1.0, v2, 1.0
	v_mul_f32_e32 v8, v3, v7
	v_fma_f32 v9, -v6, v8, v3
	v_fmac_f32_e32 v8, v9, v7
	v_pk_add_f32 v[4:5], v[4:5], 1.0 op_sel_hi:[1,0]
	v_fma_f32 v3, -v6, v8, v3
	v_div_scale_f32 v6, s[4:5], v5, v5, 1.0
	v_rcp_f32_e32 v9, v6
	v_div_fmas_f32 v3, v3, v7, v8
	v_div_fixup_f32 v2, v3, v2, 1.0
	v_cvt_pk_bf16_f32 v0, v2, v0
	v_fma_f32 v2, -v6, v9, 1.0
	v_fmac_f32_e32 v9, v2, v9
	v_div_scale_f32 v2, vcc, 1.0, v5, 1.0
	v_mul_f32_e32 v3, v2, v9
	v_fma_f32 v7, -v6, v3, v2
	v_fmac_f32_e32 v3, v7, v9
	v_fma_f32 v2, -v6, v3, v2
	v_div_scale_f32 v6, s[4:5], v4, v4, 1.0
	v_rcp_f32_e32 v7, v6
	v_div_fmas_f32 v2, v2, v9, v3
	v_div_fixup_f32 v2, v2, v5, 1.0
	s_or_b32 s4, s6, s13
	v_fma_f32 v3, -v6, v7, 1.0
	v_fmac_f32_e32 v7, v3, v7
	v_div_scale_f32 v3, vcc, 1.0, v4, 1.0
	v_mul_f32_e32 v5, v3, v7
	v_fma_f32 v8, -v6, v5, v3
	v_fmac_f32_e32 v5, v8, v7
	v_fma_f32 v3, -v6, v5, v3
	v_div_fmas_f32 v3, v3, v7, v5
	v_div_fixup_f32 v3, v3, v4, 1.0
	v_cvt_pk_bf16_f32 v2, v3, v2
	v_mov_b32_e32 v3, v133
	ds_write2st64_b32 v135, v0, v2 offset0:120 offset1:124
	s_mov_b32 s15, 0xfffffc0
	v_lshlrev_b32_e32 v0, 3, v3
	v_ashrrev_i32_e32 v4, 3, v3
	v_and_b32_e32 v156, 56, v0
	v_add_u32_e32 v0, 0x100, v3
	v_mul_lo_u32 v174, v4, s34
	v_lshlrev_b32_e32 v175, 9, v4
	v_ashrrev_i32_e32 v5, 3, v0
	v_add_u32_e32 v6, 0x200, v3
	v_mul_lo_u32 v4, v4, s21
	v_ashrrev_i32_e32 v6, 3, v6
	v_add_u32_e32 v7, 0x300, v3
	v_add_lshl_u32 v182, v4, v156, 1
	v_mul_lo_u32 v4, v5, s21
	v_ashrrev_i32_e32 v7, 3, v7
	v_add_lshl_u32 v183, v4, v156, 1
	v_mul_lo_u32 v4, v6, s21
	v_add_lshl_u32 v213, v4, v156, 1
	v_mul_lo_u32 v4, v7, s21
	v_and_b32_e32 v2, 31, v3
	v_add_lshl_u32 v214, v4, v156, 1
	v_lshrrev_b32_e32 v4, 1, v3
	s_add_u32 s4, s42, s4
	v_mul_lo_u32 v176, v5, s34
	v_lshlrev_b32_e32 v177, 9, v5
	v_and_or_b32 v5, v4, s15, v2
	v_and_b32_e32 v2, 16, v4
	s_addc_u32 s5, s43, 0
	s_lshl_b32 s6, s12, 10
	v_mad_u64_u32 v[158:159], s[16:17], v5, s37, v[2:3]
	v_and_b32_e32 v3, 0x5f, v3
	s_add_u32 s6, s9, s6
	v_mul_lo_u32 v178, v6, s34
	v_lshlrev_b32_e32 v179, 9, v6
	v_mul_lo_u32 v180, v7, s34
	v_lshlrev_b32_e32 v181, 9, v7
	v_mad_u32_u24 v159, v3, s37, v2
	v_mov_b32_e32 v2, 0
	s_mov_b32 s14, 1
	s_addc_u32 s7, s10, 0
	v_or_b32_e32 v162, v174, v156
	v_or_b32_e32 v160, v175, v156
	v_or_b32_e32 v0, v176, v156
	v_or_b32_e32 v164, v177, v156
	v_or_b32_e32 v166, v178, v156
	v_or_b32_e32 v168, v179, v156
	v_or_b32_e32 v170, v180, v156
	v_or_b32_e32 v172, v181, v156
	v_mov_b32_e32 v3, v2
	v_mov_b32_e32 v4, v2
	v_mov_b32_e32 v5, v2
	v_mov_b32_e32 v6, v2
	v_mov_b32_e32 v7, v2
	v_mov_b32_e32 v8, v2
	v_mov_b32_e32 v9, v2
	v_mov_b32_e32 v10, v2
	v_mov_b32_e32 v11, v2
	v_mov_b32_e32 v12, v2
	v_mov_b32_e32 v13, v2
	v_mov_b32_e32 v14, v2
	v_mov_b32_e32 v15, v2
	v_mov_b32_e32 v16, v2
	v_mov_b32_e32 v17, v2
	v_mov_b32_e32 v18, v2
	v_mov_b32_e32 v19, v2
	v_mov_b32_e32 v20, v2
	v_mov_b32_e32 v21, v2
	v_mov_b32_e32 v22, v2
	v_mov_b32_e32 v23, v2
	v_mov_b32_e32 v24, v2
	v_mov_b32_e32 v25, v2
	v_mov_b32_e32 v26, v2
	v_mov_b32_e32 v27, v2
	v_mov_b32_e32 v28, v2
	v_mov_b32_e32 v29, v2
	v_mov_b32_e32 v30, v2
	v_mov_b32_e32 v31, v2
	v_mov_b32_e32 v32, v2
	v_mov_b32_e32 v33, v2
	v_mov_b32_e32 v34, v2
	v_mov_b32_e32 v35, v2
	v_mov_b32_e32 v36, v2
	v_mov_b32_e32 v37, v2
	v_mov_b32_e32 v38, v2
	v_mov_b32_e32 v39, v2
	v_mov_b32_e32 v40, v2
	v_mov_b32_e32 v41, v2
	v_mov_b32_e32 v42, v2
	v_mov_b32_e32 v43, v2
	v_mov_b32_e32 v44, v2
	v_mov_b32_e32 v45, v2
	v_mov_b32_e32 v46, v2
	v_mov_b32_e32 v47, v2
	v_mov_b32_e32 v48, v2
	v_mov_b32_e32 v49, v2
	v_mov_b32_e32 v50, v2
	v_mov_b32_e32 v51, v2
	v_mov_b32_e32 v52, v2
	v_mov_b32_e32 v53, v2
	v_mov_b32_e32 v54, v2
	v_mov_b32_e32 v55, v2
	v_mov_b32_e32 v56, v2
	v_mov_b32_e32 v57, v2
	v_mov_b32_e32 v58, v2
	v_mov_b32_e32 v59, v2
	v_mov_b32_e32 v60, v2
	v_mov_b32_e32 v61, v2
	v_mov_b32_e32 v62, v2
	v_mov_b32_e32 v63, v2
	v_mov_b32_e32 v64, v2
	v_mov_b32_e32 v65, v2
	v_mov_b32_e32 v163, v1
	v_mov_b32_e32 v169, v1
	v_mov_b32_e32 v165, v1
	v_mov_b32_e32 v161, v1
	v_mov_b32_e32 v167, v1
	v_mov_b32_e32 v171, v1
	v_lshl_add_u64 v[216:217], v[0:1], 1, s[6:7]
	v_mov_b32_e32 v173, v1
	v_lshl_add_u64 v[218:219], v[162:163], 1, s[6:7]
	v_lshl_add_u64 v[224:225], v[168:169], 1, s[4:5]
	v_lshl_add_u64 v[220:221], v[164:165], 1, s[4:5]
	v_lshl_add_u64 v[168:169], v[160:161], 1, s[4:5]
	v_lshl_add_u64 v[222:223], v[166:167], 1, s[6:7]
	v_lshl_add_u64 v[228:229], v[170:171], 1, s[6:7]
	v_lshl_add_u64 v[172:173], v[172:173], 1, s[4:5]
	global_load_dwordx4 v[160:163], v[216:217], off
	global_load_dwordx4 v[164:167], v[218:219], off
	s_nop 0
	global_load_dwordx4 v[168:171], v[168:169], off
	s_nop 0
	global_load_dwordx4 v[216:219], v[220:221], off
	s_nop 0
	global_load_dwordx4 v[220:223], v[222:223], off
	s_nop 0
	global_load_dwordx4 v[224:227], v[224:225], off
	s_nop 0
	global_load_dwordx4 v[228:231], v[228:229], off
	s_nop 0
	global_load_dwordx4 v[232:235], v[172:173], off
